# v47 + attention: splat(-m) of row group B kept persistent in v[240:255] as MFMA srcC (16 fewer v_mov per sub-tile)
# baseline (speedup 1.0000x reference)
; __device__ __forceinline__ void attn_phase(LAS unsigned char* lds, const bf16_t* QKVZ, bf16_t* AO, const float* sink) {
;     ...
;         const int item = ATT_ITEM(k);
;         int b, kh, qrow0, nblk; bool isctx;
;         if (item < 512) { b = item >> 7; nblk = (item >> 2) & 31; kh = item & 3; qrow0 = b * SEQ + nblk * 128; isctx = false; }
;         else { const int r = item - 512; b = r >> 3; kh = r & 3; qrow0 = NLAT + b * CTXL + ((r >> 2) & 1) * 128; isctx = true; nblk = 0; }
;         const int head = kh * 4 + hq;
;         bf16x8 Qf[2][4];
; #pragma unroll
;         for (int qt = 0; qt < 2; ++qt)
; #pragma unroll
;             for (int ks = 0; ks < 4; ++ks) Qf[qt][ks] = Qn[qt][ks];
;         f32x16 O[2][2];
; #pragma unroll
;         for (int dt = 0; dt < 2; ++dt)
; #pragma unroll
;             for (int qt = 0; qt < 2; ++qt)
; #pragma unroll
;                 for (int i = 0; i < 16; ++i) O[dt][qt][i] = 0.f;
;         const float sk = sink[head] * LOG2E;
;         float m_[2] = {sk, sk}, l_[2]; l_[0] = l_[1] = (hh == 0) ? 1.0f : 0.0f;
;         const int ntiles = isctx ? 2 : 5;
;         int tcur = (!isctx && nblk == 0) ? 1 : 0;
.LBB0_298:
	s_and_b32 s1, s2, 3
	s_lshl_b32 s2, s1, 2
	s_or_b32 s67, s2, s57
	s_lshl_b32 s2, s67, 2
	v_mov_b32_e32 v1, s2
	global_load_dword v80, v1, s[52:53]
	v_sub_co_u32_e64 v205, s[42:43], s0, 1
	s_waitcnt vmcnt(1)
	v_mov_b32_e32 v14, v0
	v_mov_b32_e32 v15, v0
	s_and_b64 s[42:43], s[24:25], s[42:43]
	v_mov_b32_e32 v1, v0
	v_mov_b32_e32 v2, v0
	v_mov_b32_e32 v3, v0
	v_mov_b32_e32 v4, v0
	v_mov_b32_e32 v5, v0
	v_mov_b32_e32 v6, v0
	v_mov_b32_e32 v7, v0
	v_mov_b32_e32 v8, v0
	v_mov_b32_e32 v9, v0
	v_mov_b32_e32 v10, v0
	v_mov_b32_e32 v11, v0
	v_mov_b32_e32 v12, v0
	v_mov_b32_e32 v13, v0
	v_mov_b64_e32 v[30:31], v[14:15]
	v_mov_b64_e32 v[62:63], v[14:15]
	v_mov_b64_e32 v[46:47], v[14:15]
	v_mov_b64_e32 v[78:79], v[14:15]
	s_cmp_eq_u32 s0, 31
	v_cndmask_b32_e64 v81, 0, 1, s[42:43]
	v_mov_b64_e32 v[28:29], v[12:13]
	v_mov_b64_e32 v[26:27], v[10:11]
	v_mov_b64_e32 v[24:25], v[8:9]
	v_mov_b64_e32 v[22:23], v[6:7]
	v_mov_b64_e32 v[20:21], v[4:5]
	v_mov_b64_e32 v[18:19], v[2:3]
	v_mov_b64_e32 v[16:17], v[0:1]
	v_mov_b64_e32 v[60:61], v[12:13]
	v_mov_b64_e32 v[58:59], v[10:11]
	v_mov_b64_e32 v[56:57], v[8:9]
	v_mov_b64_e32 v[54:55], v[6:7]
	v_mov_b64_e32 v[52:53], v[4:5]
	v_mov_b64_e32 v[50:51], v[2:3]
	v_mov_b64_e32 v[48:49], v[0:1]
	v_mov_b64_e32 v[44:45], v[12:13]
	v_mov_b64_e32 v[42:43], v[10:11]
	v_mov_b64_e32 v[40:41], v[8:9]
	v_mov_b64_e32 v[38:39], v[6:7]
	v_mov_b64_e32 v[36:37], v[4:5]
	v_mov_b64_e32 v[34:35], v[2:3]
	v_mov_b64_e32 v[32:33], v[0:1]
	v_mov_b64_e32 v[76:77], v[12:13]
	v_mov_b64_e32 v[74:75], v[10:11]
	v_mov_b64_e32 v[72:73], v[8:9]
	v_mov_b64_e32 v[70:71], v[6:7]
	v_mov_b64_e32 v[68:69], v[4:5]
	v_mov_b64_e32 v[66:67], v[2:3]
	v_mov_b64_e32 v[64:65], v[0:1]
	s_cselect_b64 s[42:43], -1, 0
	s_lshl_b32 s22, s1, 7
	v_mov_b32_e32 v227, v210
	v_readfirstlane_b32 s2, v81
	s_add_i32 s74, s3, 0x3e80
	v_lshl_add_u64 v[2:3], v[200:201], 0, s[22:23]
	v_lshl_add_u64 v[4:5], v[202:203], 0, s[22:23]
	v_mov_b32_e32 v1, v210
	s_waitcnt vmcnt(0)
	v_mul_f32_e32 v7, 0x3fb8aa3b, v80
	v_mov_b32_e32 v9, v7
	v_xor_b32_e32 v240, 0x80000000, v7
	v_mov_b32_e32 v241, v240
	v_mov_b32_e32 v242, v240
	v_mov_b32_e32 v243, v240
	v_mov_b32_e32 v244, v240
	v_mov_b32_e32 v245, v240
	v_mov_b32_e32 v246, v240
	v_mov_b32_e32 v247, v240
	v_mov_b32_e32 v248, v240
	v_mov_b32_e32 v249, v240
	v_mov_b32_e32 v250, v240
	v_mov_b32_e32 v251, v240
	v_mov_b32_e32 v252, v240
	v_mov_b32_e32 v253, v240
	v_mov_b32_e32 v254, v240
	v_mov_b32_e32 v255, v240

; #define LAS __attribute__((address_space(3)))
; #define MFMA32(a, b, c) __builtin_amdgcn_mfma_f32_32x32x16_bf16((a), (b), (c), 0, 0, 0)
; __device__ __forceinline__ void attn_phase(LAS unsigned char* lds, const bf16_t* QKVZ, bf16_t* AO, const float* sink) {
;     ...
;             for (int sub = 0; sub < 2; ++sub) {
;                 if ((mode == 1 && sub < qh) || (mode == 2 && sub > qh)) continue;
;                 f32x16 S[2][2];
; #pragma unroll
;                 for (int kt = 0; kt < 2; ++kt)
; #pragma unroll
;                     for (int qt = 0; qt < 2; ++qt)
; #pragma unroll
;                         for (int i = 0; i < 16; ++i) S[kt][qt][i] = -m_[qt];
; #pragma unroll
;                 for (int kt = 0; kt < 2; ++kt)
; #pragma unroll
;                     for (int ks = 0; ks < 4; ++ks) {
;                         const bf16x8 Kf = *(const LAS bf16x8*)(Ks + (64 * sub + 32 * kt + ql) * KS_PITCH + (16 * ks + 8 * hh) * 2);
;                         S[kt][0] = MFMA32(Kf, Qf[0][ks], S[kt][0]);
;                         S[kt][1] = MFMA32(Kf, Qf[1][ks], S[kt][1]);
;                     }
;                 if (mode) {
; #pragma unroll
;                     for (int kt = 0; kt < 2; ++kt)
; #pragma unroll
;                         for (int qt = 0; qt < 2; ++qt)
; #pragma unroll
;                             for (int i = 0; i < 16; ++i) {
;                                 const int j = 64 * sub + 32 * kt + 8 * (i >> 2) + 4 * hh + (i & 3), iq = 64 * qh + 32 * qt + ql;
;                                 const bool valid = (mode == 1) ? (j >= iq) : (j <= iq);
;                                 S[kt][qt][i] = valid ? S[kt][qt][i] : -1e30f;
;                             }
.LBB0_311:
	s_cmp_lt_i32 s75, s58
	s_cselect_b64 s[0:1], -1, 0
	s_and_b64 s[0:1], s[2:3], s[0:1]
	s_cmp_gt_i32 s75, s58
	s_cselect_b64 s[76:77], -1, 0
	s_and_b64 s[76:77], s[48:49], s[76:77]
	s_or_b64 s[0:1], s[0:1], s[76:77]
	s_and_b64 vcc, exec, s[0:1]
	s_cbranch_vccnz .LBB0_310
	s_lshl_b32 s0, s75, 6
	v_or_b32_e32 v6, s0, v193
	v_mad_u32_u24 v6, v6, s61, v10
	ds_read_b128 v[12:15], v6
	ds_read_b128 v[228:231], v6 offset:32
	v_xor_b32_e32 v96, 0x80000000, v9
	v_mov_b32_e32 v97, v96
	v_mov_b32_e32 v98, v96
	v_mov_b32_e32 v99, v96
	v_mov_b32_e32 v100, v96
	v_mov_b32_e32 v101, v96
	v_mov_b32_e32 v102, v96
	v_mov_b32_e32 v103, v96
	v_mov_b32_e32 v104, v96
	v_mov_b32_e32 v105, v96
	v_mov_b32_e32 v106, v96
	v_mov_b32_e32 v107, v96
	v_mov_b32_e32 v108, v96
	v_mov_b32_e32 v109, v96
	v_mov_b32_e32 v110, v96
	v_mov_b32_e32 v111, v96
	s_waitcnt lgkmcnt(1)
	v_mfma_f32_32x32x16_bf16 v[128:143], v[12:15], v[144:147], v[96:111]
	s_andn2_b64 vcc, exec, s[50:51]
	v_mfma_f32_32x32x16_bf16 v[112:127], v[12:15], v[160:163], v[240:255]
	s_waitcnt lgkmcnt(0)
	v_mfma_f32_32x32x16_bf16 v[128:143], v[228:231], v[148:151], v[128:143]
	v_mfma_f32_32x32x16_bf16 v[112:127], v[228:231], v[164:167], v[112:127]
	ds_read_b128 v[12:15], v6 offset:64
	ds_read_b128 v[228:231], v6 offset:96
	s_waitcnt lgkmcnt(1)
	v_mfma_f32_32x32x16_bf16 v[128:143], v[12:15], v[152:155], v[128:143]
	v_mfma_f32_32x32x16_bf16 v[112:127], v[12:15], v[168:171], v[112:127]
	s_waitcnt lgkmcnt(0)
	v_mfma_f32_32x32x16_bf16 v[128:143], v[228:231], v[156:159], v[128:143]
	v_mfma_f32_32x32x16_bf16 v[112:127], v[228:231], v[172:175], v[112:127]
	ds_read_b128 v[12:15], v6 offset:4608
	ds_read_b128 v[228:231], v6 offset:4640
	s_waitcnt lgkmcnt(1)
	v_mfma_f32_32x32x16_bf16 v[96:111], v[12:15], v[144:147], v[96:111]
	v_mfma_f32_32x32x16_bf16 v[80:95], v[12:15], v[160:163], v[240:255]
	s_waitcnt lgkmcnt(0)
	v_mfma_f32_32x32x16_bf16 v[96:111], v[228:231], v[148:151], v[96:111]
	v_mfma_f32_32x32x16_bf16 v[80:95], v[228:231], v[164:167], v[80:95]
	ds_read_b128 v[12:15], v6 offset:4672
	ds_read_b128 v[228:231], v6 offset:4704
	s_waitcnt lgkmcnt(1)
	v_mfma_f32_32x32x16_bf16 v[96:111], v[12:15], v[152:155], v[96:111]
	v_mfma_f32_32x32x16_bf16 v[80:95], v[12:15], v[168:171], v[80:95]
	s_waitcnt lgkmcnt(0)
	v_mfma_f32_32x32x16_bf16 v[96:111], v[228:231], v[156:159], v[96:111]
	v_mfma_f32_32x32x16_bf16 v[80:95], v[228:231], v[172:175], v[80:95]
	s_cbranch_vccnz .LBB0_314
	s_cmp_lg_u32 s75, s58
	s_cbranch_scc1 .LBB0_314
	v_or_b32_e32 v6, s0, v214
	v_sub_u32_e32 v8, v215, v6
	s_and_b64 vcc, exec, s[2:3]
	s_nop 4
	s_cbranch_vccz .Lattn_mask_m2
	v_cmp_ge_i32_e64 s[0:1], 0, v8
	v_cmp_ge_i32_e64 s[96:97], 1, v8
	v_cmp_ge_i32_e64 s[98:99], 2, v8
	v_cmp_ge_i32_e64 s[100:101], 3, v8
	v_cndmask_b32_e64 v128, v226, v128, s[0:1]
	v_cndmask_b32_e64 v80, v226, v80, s[0:1]
	v_cndmask_b32_e64 v129, v226, v129, s[96:97]
	v_cndmask_b32_e64 v81, v226, v81, s[96:97]
	v_cndmask_b32_e64 v130, v226, v130, s[98:99]
	v_cndmask_b32_e64 v82, v226, v82, s[98:99]
	v_cndmask_b32_e64 v131, v226, v131, s[100:101]
	v_cndmask_b32_e64 v83, v226, v83, s[100:101]
	v_cmp_ge_i32_e64 s[0:1], 8, v8
	v_cmp_ge_i32_e64 s[96:97], 9, v8
	v_cmp_ge_i32_e64 s[98:99], 10, v8
	v_cmp_ge_i32_e64 s[100:101], 11, v8
	v_cndmask_b32_e64 v132, v226, v132, s[0:1]
	v_cndmask_b32_e64 v84, v226, v84, s[0:1]
	v_cndmask_b32_e64 v133, v226, v133, s[96:97]
	v_cndmask_b32_e64 v85, v226, v85, s[96:97]
	v_cndmask_b32_e64 v134, v226, v134, s[98:99]
	v_cndmask_b32_e64 v86, v226, v86, s[98:99]
	v_cndmask_b32_e64 v135, v226, v135, s[100:101]
	v_cndmask_b32_e64 v87, v226, v87, s[100:101]
	v_cmp_ge_i32_e64 s[0:1], 16, v8
	v_cmp_ge_i32_e64 s[96:97], 17, v8
	v_cmp_ge_i32_e64 s[98:99], 18, v8
	v_cmp_ge_i32_e64 s[100:101], 19, v8
	v_cndmask_b32_e64 v136, v226, v136, s[0:1]
	v_cndmask_b32_e64 v88, v226, v88, s[0:1]
	v_cndmask_b32_e64 v137, v226, v137, s[96:97]
	v_cndmask_b32_e64 v89, v226, v89, s[96:97]
	v_cndmask_b32_e64 v138, v226, v138, s[98:99]
	v_cndmask_b32_e64 v90, v226, v90, s[98:99]
	v_cndmask_b32_e64 v139, v226, v139, s[100:101]
	v_cndmask_b32_e64 v91, v226, v91, s[100:101]
	v_cmp_ge_i32_e64 s[0:1], 24, v8
	v_cmp_ge_i32_e64 s[96:97], 25, v8
	v_cmp_ge_i32_e64 s[98:99], 26, v8
	v_cmp_ge_i32_e64 s[100:101], 27, v8
	v_cndmask_b32_e64 v140, v226, v140, s[0:1]
	v_cndmask_b32_e64 v92, v226, v92, s[0:1]
	v_cndmask_b32_e64 v141, v226, v141, s[96:97]
	v_cndmask_b32_e64 v93, v226, v93, s[96:97]
	v_cndmask_b32_e64 v142, v226, v142, s[98:99]
	v_cndmask_b32_e64 v94, v226, v94, s[98:99]
	v_cndmask_b32_e64 v143, v226, v143, s[100:101]
	v_cndmask_b32_e64 v95, v226, v95, s[100:101]
	v_mov_b32_e32 v112, v226
	v_mov_b32_e32 v113, v226
	v_mov_b32_e32 v114, v226
	v_mov_b32_e32 v115, v226
	v_mov_b32_e32 v116, v226
	v_mov_b32_e32 v117, v226
	v_mov_b32_e32 v118, v226
	v_mov_b32_e32 v119, v226
	v_mov_b32_e32 v120, v226
	v_mov_b32_e32 v121, v226
	v_mov_b32_e32 v122, v226
	v_mov_b32_e32 v123, v226
	v_mov_b32_e32 v124, v226
	v_mov_b32_e32 v125, v226
	v_mov_b32_e32 v126, v226
	v_mov_b32_e32 v127, v226
	s_branch .LBB0_314

; __device__ __forceinline__ float fast_exp2(float x) { return __builtin_amdgcn_exp2f(x); }
; __device__ __forceinline__ void attn_phase(LAS unsigned char* lds, const bf16_t* QKVZ, bf16_t* AO, const float* sink) {
;     ...
;                 for (int qt = 0; qt < 2; ++qt) {
;                     float mx = S[0][qt][0];
; #pragma unroll
;                     for (int kt = 0; kt < 2; ++kt)
; #pragma unroll
;                         for (int i = 0; i < 16; ++i) mx = fmaxf(mx, S[kt][qt][i]);
;                     { const auto rr = __builtin_amdgcn_permlane32_swap(__float_as_uint(mx), __float_as_uint(mx), false, false);
;                       mx = fmaxf(__uint_as_float(rr[0]), __uint_as_float(rr[1])); }
;                     float alpha = 1.0f;
;                     if (!__builtin_expect(__all(mx <= ATT_THR), 1)) {
;                         const float dlt = fmaxf(mx, 0.0f);
;                         alpha = fast_exp2(-dlt); m_[qt] += dlt;
; #pragma unroll
;                         for (int i = 0; i < 16; ++i) { O[0][qt][i] *= alpha; O[1][qt][i] *= alpha; }
; #pragma unroll
;                         for (int kt = 0; kt < 2; ++kt)
; #pragma unroll
;                             for (int i = 0; i < 16; ++i) S[kt][qt][i] -= dlt;
;                     }
.LBB0_316:
	v_max_f32_e32 v12, v112, v113
	v_max3_f32 v12, v12, v114, v115
	v_max3_f32 v12, v12, v116, v117
	v_max3_f32 v12, v12, v118, v119
	v_max3_f32 v12, v12, v120, v121
	v_max3_f32 v12, v12, v122, v123
	v_max3_f32 v12, v12, v124, v125
	v_max3_f32 v12, v12, v126, v127
	v_max3_f32 v12, v12, v80, v81
	v_max3_f32 v12, v12, v82, v83
	v_max3_f32 v12, v12, v84, v85
	v_max3_f32 v12, v12, v86, v87
	v_max3_f32 v12, v12, v88, v89
	v_max3_f32 v12, v12, v90, v91
	v_max3_f32 v12, v12, v92, v93
	v_max3_f32 v12, v12, v94, v95
	v_mov_b32_e32 v13, v12
	s_nop 1
	v_permlane32_swap_b32_e32 v12, v13
	v_max_f32_e32 v12, v12, v13
	v_cmp_ge_f32_e32 vcc, s64, v12
	s_cmp_eq_u64 vcc, exec
	s_cbranch_scc1 .LBB0_309
	v_max_f32_e32 v6, v12, v12
	v_max_f32_e32 v12, 0, v6
	v_exp_f32_e64 v6, -v12
	v_add_f32_e32 v7, v7, v12
	v_xor_b32_e32 v240, 0x80000000, v7
	v_mov_b32_e32 v241, v240
	v_mov_b32_e32 v242, v240
	v_mov_b32_e32 v243, v240
	v_mov_b32_e32 v244, v240
	v_mov_b32_e32 v245, v240
	v_mov_b32_e32 v246, v240
	v_mov_b32_e32 v247, v240
	v_mov_b32_e32 v248, v240
	v_mov_b32_e32 v249, v240
	v_mov_b32_e32 v250, v240
	v_mov_b32_e32 v251, v240
	v_mov_b32_e32 v252, v240
	v_mov_b32_e32 v253, v240
	v_mov_b32_e32 v254, v240
	v_mov_b32_e32 v255, v240
	v_pk_add_f32 v[112:113], v[112:113], v[12:13] op_sel_hi:[1,0] neg_lo:[0,1] neg_hi:[0,1]
	v_pk_add_f32 v[114:115], v[114:115], v[12:13] op_sel_hi:[1,0] neg_lo:[0,1] neg_hi:[0,1]
	v_pk_mul_f32 v[46:47], v[46:47], v[6:7] op_sel_hi:[1,0]
	v_pk_mul_f32 v[44:45], v[44:45], v[6:7] op_sel_hi:[1,0]
	v_pk_mul_f32 v[42:43], v[42:43], v[6:7] op_sel_hi:[1,0]
	v_pk_mul_f32 v[40:41], v[40:41], v[6:7] op_sel_hi:[1,0]
	v_pk_mul_f32 v[38:39], v[38:39], v[6:7] op_sel_hi:[1,0]
	v_pk_mul_f32 v[36:37], v[36:37], v[6:7] op_sel_hi:[1,0]
	v_pk_mul_f32 v[34:35], v[34:35], v[6:7] op_sel_hi:[1,0]
	v_pk_mul_f32 v[32:33], v[32:33], v[6:7] op_sel_hi:[1,0]
	v_pk_mul_f32 v[30:31], v[30:31], v[6:7] op_sel_hi:[1,0]
	v_pk_mul_f32 v[28:29], v[28:29], v[6:7] op_sel_hi:[1,0]
	v_pk_mul_f32 v[26:27], v[26:27], v[6:7] op_sel_hi:[1,0]
	v_pk_mul_f32 v[24:25], v[24:25], v[6:7] op_sel_hi:[1,0]
	v_pk_mul_f32 v[22:23], v[22:23], v[6:7] op_sel_hi:[1,0]
	v_pk_mul_f32 v[20:21], v[20:21], v[6:7] op_sel_hi:[1,0]
	v_pk_mul_f32 v[18:19], v[18:19], v[6:7] op_sel_hi:[1,0]
	v_pk_mul_f32 v[16:17], v[16:17], v[6:7] op_sel_hi:[1,0]
	v_pk_add_f32 v[116:117], v[116:117], v[12:13] op_sel_hi:[1,0] neg_lo:[0,1] neg_hi:[0,1]
	v_pk_add_f32 v[118:119], v[118:119], v[12:13] op_sel_hi:[1,0] neg_lo:[0,1] neg_hi:[0,1]
	v_pk_add_f32 v[120:121], v[120:121], v[12:13] op_sel_hi:[1,0] neg_lo:[0,1] neg_hi:[0,1]
	v_pk_add_f32 v[122:123], v[122:123], v[12:13] op_sel_hi:[1,0] neg_lo:[0,1] neg_hi:[0,1]
	v_pk_add_f32 v[124:125], v[124:125], v[12:13] op_sel_hi:[1,0] neg_lo:[0,1] neg_hi:[0,1]
	v_pk_add_f32 v[126:127], v[126:127], v[12:13] op_sel_hi:[1,0] neg_lo:[0,1] neg_hi:[0,1]
	v_pk_add_f32 v[80:81], v[80:81], v[12:13] op_sel_hi:[1,0] neg_lo:[0,1] neg_hi:[0,1]
	v_pk_add_f32 v[82:83], v[82:83], v[12:13] op_sel_hi:[1,0] neg_lo:[0,1] neg_hi:[0,1]
	v_pk_add_f32 v[84:85], v[84:85], v[12:13] op_sel_hi:[1,0] neg_lo:[0,1] neg_hi:[0,1]
	v_pk_add_f32 v[86:87], v[86:87], v[12:13] op_sel_hi:[1,0] neg_lo:[0,1] neg_hi:[0,1]
	v_pk_add_f32 v[88:89], v[88:89], v[12:13] op_sel_hi:[1,0] neg_lo:[0,1] neg_hi:[0,1]
	v_pk_add_f32 v[90:91], v[90:91], v[12:13] op_sel_hi:[1,0] neg_lo:[0,1] neg_hi:[0,1]
	v_pk_add_f32 v[92:93], v[92:93], v[12:13] op_sel_hi:[1,0] neg_lo:[0,1] neg_hi:[0,1]
	v_pk_add_f32 v[94:95], v[94:95], v[12:13] op_sel_hi:[1,0] neg_lo:[0,1] neg_hi:[0,1]
	s_branch .LBB0_309
